# hyena ctx direct conv: second-sum loops unrolled x8 with per-lane k, first-sum reads hoisted to one wait; on top of barrier TOPGEN polling
# speedup vs baseline: 1.0115x; 1.0115x over previous
.LBB0_1771:
	ds_read_b128 v[44:47], v12
	ds_read_b128 v[48:51], v12 offset:16
	ds_read2_b32 v[52:53], v10 offset0:6 offset1:7
	ds_read2_b32 v[120:121], v10 offset0:4 offset1:5
	ds_read2_b32 v[122:123], v10 offset0:2 offset1:3
	ds_read2_b32 v[124:125], v10 offset1:1
	s_add_i32 s19, s19, 8
	v_cmp_eq_u32_e32 vcc, s19, v20
	v_add_u32_e32 v12, 32, v12
	s_or_b64 s[30:31], vcc, s[30:31]
	s_waitcnt lgkmcnt(0)
	v_fmac_f32_e32 v42, v44, v53
	v_fmac_f32_e32 v42, v45, v52
	v_fmac_f32_e32 v42, v46, v121
	v_fmac_f32_e32 v42, v47, v120
	v_fmac_f32_e32 v42, v48, v123
	v_fmac_f32_e32 v42, v49, v122
	v_subrev_u32_e32 v10, 32, v10
	v_fmac_f32_e32 v42, v50, v125
	v_fmac_f32_e32 v42, v51, v124
	s_andn2_b64 exec, exec, s[30:31]
	s_cbranch_execnz .LBB0_1771
	s_or_b64 exec, exec, s[30:31]
	v_mov_b32_e32 v10, v20

.LBB0_1777:
	s_or_b64 exec, exec, s[28:29]
	s_mov_b32 s19, 0
	s_mov_b64 s[28:29], 0
	v_mov_b32_e32 v10, v18
	v_mov_b32_e32 v100, s19
	s_movk_i32 s100, 0x1004
	s_mov_b64 s[98:99], exec
	v_cmp_gt_i32_e32 vcc, 0xf7, v10
	s_and_b64 exec, exec, vcc
	s_cbranch_execz .Lhc0_rem
.Lhc0_main:
	v_add3_u32 v101, v100, v25, s100
	v_add_u32_e32 v102, 0x404, v100
	ds_read2_b32 v[104:105], v101 offset1:1
	ds_read2_b32 v[106:107], v101 offset0:2 offset1:3
	ds_read2_b32 v[108:109], v101 offset0:4 offset1:5
	ds_read2_b32 v[110:111], v101 offset0:6 offset1:7
	ds_read2_b32 v[112:113], v102 offset1:1
	ds_read2_b32 v[114:115], v102 offset0:2 offset1:3
	ds_read2_b32 v[116:117], v102 offset0:4 offset1:5
	ds_read2_b32 v[118:119], v102 offset0:6 offset1:7
	v_add_u32_e32 v10, 8, v10
	v_add_u32_e32 v100, 32, v100
	v_cmp_gt_i32_e32 vcc, 0xf7, v10
	s_waitcnt lgkmcnt(0)
	v_fmac_f32_e32 v42, v104, v112
	v_fmac_f32_e32 v42, v105, v113
	v_fmac_f32_e32 v42, v106, v114
	v_fmac_f32_e32 v42, v107, v115
	v_fmac_f32_e32 v42, v108, v116
	v_fmac_f32_e32 v42, v109, v117
	v_fmac_f32_e32 v42, v110, v118
	v_fmac_f32_e32 v42, v111, v119
	s_and_b64 exec, exec, vcc
	s_cbranch_execnz .Lhc0_main
.Lhc0_rem:
	s_mov_b64 exec, s[98:99]
	v_cmp_gt_i32_e32 vcc, 0xfe, v10
	s_and_b64 exec, exec, vcc
	s_cbranch_execz .Lhc0_end
.Lhc0_rl:
	v_add3_u32 v101, v100, v25, s100
	v_add_u32_e32 v102, 0x404, v100
	ds_read_b32 v101, v101
	ds_read_b32 v102, v102
	v_add_u32_e32 v10, 1, v10
	v_add_u32_e32 v100, 4, v100
	v_cmp_gt_i32_e32 vcc, 0xfe, v10
	s_waitcnt lgkmcnt(0)
	v_fmac_f32_e32 v42, v101, v102
	s_and_b64 exec, exec, vcc
	s_cbranch_execnz .Lhc0_rl
.Lhc0_end:
	s_mov_b64 exec, s[98:99]
	s_or_b64 exec, exec, s[28:29]
	v_add_u32_e32 v12, 0x200, v8
	v_ashrrev_i32_e32 v13, 31, v12
	v_lshlrev_b64 v[12:13], 9, v[12:13]
	v_lshl_add_u64 v[12:13], v[2:3], 0, v[12:13]
	global_load_ushort v10, v[12:13], off
	s_waitcnt vmcnt(0)
	v_lshlrev_b32_e32 v10, 16, v10
	v_fma_f32 v44, v11, v10, v43
	s_and_saveexec_b64 s[28:29], s[16:17]
	s_cbranch_execz .LBB0_1781
	global_load_ushort v10, v[12:13], off offset:-2
	global_load_dword v45, v1, s[26:27]
	s_waitcnt vmcnt(1)
	v_lshlrev_b32_e32 v10, 16, v10
	s_waitcnt vmcnt(0)
	v_fmac_f32_e32 v44, v45, v10

.LBB0_1782:
	ds_read_b128 v[50:53], v10
	ds_read_b128 v[54:57], v10 offset:16
	ds_read2_b32 v[58:59], v48 offset0:6 offset1:7
	ds_read2_b32 v[120:121], v48 offset0:4 offset1:5
	ds_read2_b32 v[122:123], v48 offset0:2 offset1:3
	ds_read2_b32 v[124:125], v48 offset1:1
	s_add_i32 s19, s19, 8
	v_mov_b32_e32 v47, v49
	v_cmp_eq_u32_e32 vcc, s19, v21
	v_add_u32_e32 v10, 32, v10
	s_waitcnt lgkmcnt(0)
	v_fmac_f32_e32 v45, v50, v59
	v_fmac_f32_e32 v45, v51, v58
	v_subrev_u32_e32 v49, 32, v47
	s_or_b64 s[28:29], vcc, s[28:29]
	v_fmac_f32_e32 v45, v52, v121
	v_fmac_f32_e32 v45, v53, v120
	v_fmac_f32_e32 v45, v54, v123
	v_fmac_f32_e32 v45, v55, v122
	v_subrev_u32_e32 v48, 32, v48
	v_fmac_f32_e32 v45, v56, v125
	v_fmac_f32_e32 v45, v57, v124
	s_andn2_b64 exec, exec, s[28:29]
	s_cbranch_execnz .LBB0_1782
	s_or_b64 exec, exec, s[28:29]
	s_and_saveexec_b64 s[28:29], s[14:15]
	s_cbranch_execz .LBB0_1787
	s_mov_b32 s19, 0
	s_mov_b64 s[30:31], 0

.LBB0_1787:
	s_or_b64 exec, exec, s[28:29]
	s_and_saveexec_b64 s[28:29], s[8:9]
	s_cbranch_execz .LBB0_1791
	s_mov_b32 s19, 0
	s_mov_b64 s[30:31], 0
	v_mov_b32_e32 v10, v29
	v_mov_b32_e32 v100, s19
	s_movk_i32 s100, 0x1204
	s_mov_b64 s[98:99], exec
	v_cmp_gt_i32_e32 vcc, 0xf7, v10
	s_and_b64 exec, exec, vcc
	s_cbranch_execz .Lhc1_rem
.Lhc1_main:
	v_add3_u32 v101, v100, v25, s100
	v_add_u32_e32 v102, 0x404, v100
	ds_read2_b32 v[104:105], v101 offset1:1
	ds_read2_b32 v[106:107], v101 offset0:2 offset1:3
	ds_read2_b32 v[108:109], v101 offset0:4 offset1:5
	ds_read2_b32 v[110:111], v101 offset0:6 offset1:7
	ds_read2_b32 v[112:113], v102 offset1:1
	ds_read2_b32 v[114:115], v102 offset0:2 offset1:3
	ds_read2_b32 v[116:117], v102 offset0:4 offset1:5
	ds_read2_b32 v[118:119], v102 offset0:6 offset1:7
	v_add_u32_e32 v10, 8, v10
	v_add_u32_e32 v100, 32, v100
	v_cmp_gt_i32_e32 vcc, 0xf7, v10
	s_waitcnt lgkmcnt(0)
	v_fmac_f32_e32 v45, v104, v112
	v_fmac_f32_e32 v45, v105, v113
	v_fmac_f32_e32 v45, v106, v114
	v_fmac_f32_e32 v45, v107, v115
	v_fmac_f32_e32 v45, v108, v116
	v_fmac_f32_e32 v45, v109, v117
	v_fmac_f32_e32 v45, v110, v118
	v_fmac_f32_e32 v45, v111, v119
	s_and_b64 exec, exec, vcc
	s_cbranch_execnz .Lhc1_main

.Lhc1_rl:
	v_add3_u32 v101, v100, v25, s100
	v_add_u32_e32 v102, 0x404, v100
	ds_read_b32 v101, v101
	ds_read_b32 v102, v102
	v_add_u32_e32 v10, 1, v10
	v_add_u32_e32 v100, 4, v100
	v_cmp_gt_i32_e32 vcc, 0xfe, v10
	s_waitcnt lgkmcnt(0)
	v_fmac_f32_e32 v45, v101, v102
	s_and_b64 exec, exec, vcc
	s_cbranch_execnz .Lhc1_rl
.Lhc1_end:
	s_mov_b64 exec, s[98:99]
	s_or_b64 exec, exec, s[30:31]

.LBB0_1795:
	ds_read_b128 v[44:47], v12
	ds_read_b128 v[48:51], v12 offset:16
	ds_read2_b32 v[52:53], v10 offset0:6 offset1:7
	ds_read2_b32 v[120:121], v10 offset0:4 offset1:5
	ds_read2_b32 v[122:123], v10 offset0:2 offset1:3
	ds_read2_b32 v[124:125], v10 offset1:1
	s_add_i32 s19, s19, 8
	v_cmp_eq_u32_e32 vcc, s19, v20
	v_add_u32_e32 v12, 32, v12
	s_or_b64 s[24:25], vcc, s[24:25]
	s_waitcnt lgkmcnt(0)
	v_fmac_f32_e32 v42, v44, v53
	v_fmac_f32_e32 v42, v45, v52
	v_fmac_f32_e32 v42, v46, v121
	v_fmac_f32_e32 v42, v47, v120
	v_fmac_f32_e32 v42, v48, v123
	v_fmac_f32_e32 v42, v49, v122
	v_subrev_u32_e32 v10, 32, v10
	v_fmac_f32_e32 v42, v50, v125
	v_fmac_f32_e32 v42, v51, v124
	s_andn2_b64 exec, exec, s[24:25]
	s_cbranch_execnz .LBB0_1795
	s_or_b64 exec, exec, s[24:25]
	v_mov_b32_e32 v10, v20

.LBB0_1801:
	s_or_b64 exec, exec, s[22:23]
	s_mov_b64 s[22:23], 0
	v_mov_b32_e32 v10, v18
	s_mov_b32 s19, s33
	v_mov_b32_e32 v100, s19
	s_movk_i32 s100, 0x400
	s_mov_b64 s[98:99], exec
	v_cmp_gt_i32_e32 vcc, 0xf7, v10
	s_and_b64 exec, exec, vcc
	s_cbranch_execz .Lhc2_rem
.Lhc2_main:
	v_add3_u32 v101, v100, v25, s100
	v_mov_b32_e32 v102, v100
	ds_read2_b32 v[104:105], v101 offset1:1
	ds_read2_b32 v[106:107], v101 offset0:2 offset1:3
	ds_read2_b32 v[108:109], v101 offset0:4 offset1:5
	ds_read2_b32 v[110:111], v101 offset0:6 offset1:7
	ds_read2_b32 v[112:113], v102 offset1:1
	ds_read2_b32 v[114:115], v102 offset0:2 offset1:3
	ds_read2_b32 v[116:117], v102 offset0:4 offset1:5
	ds_read2_b32 v[118:119], v102 offset0:6 offset1:7
	v_add_u32_e32 v10, 8, v10
	v_add_u32_e32 v100, 32, v100
	v_cmp_gt_i32_e32 vcc, 0xf7, v10
	s_waitcnt lgkmcnt(0)
	v_fmac_f32_e32 v42, v104, v112
	v_fmac_f32_e32 v42, v105, v113
	v_fmac_f32_e32 v42, v106, v114
	v_fmac_f32_e32 v42, v107, v115
	v_fmac_f32_e32 v42, v108, v116
	v_fmac_f32_e32 v42, v109, v117
	v_fmac_f32_e32 v42, v110, v118
	v_fmac_f32_e32 v42, v111, v119
	s_and_b64 exec, exec, vcc
	s_cbranch_execnz .Lhc2_main

.Lhc2_rl:
	v_add3_u32 v101, v100, v25, s100
	v_mov_b32_e32 v102, v100
	ds_read_b32 v101, v101
	ds_read_b32 v102, v102
	v_add_u32_e32 v10, 1, v10
	v_add_u32_e32 v100, 4, v100
	v_cmp_gt_i32_e32 vcc, 0xfe, v10
	s_waitcnt lgkmcnt(0)
	v_fmac_f32_e32 v42, v101, v102
	s_and_b64 exec, exec, vcc
	s_cbranch_execnz .Lhc2_rl
.Lhc2_end:
	s_mov_b64 exec, s[98:99]
	s_or_b64 exec, exec, s[22:23]
	v_add_u32_e32 v12, 0x400, v8
	v_ashrrev_i32_e32 v13, 31, v12
	v_lshlrev_b64 v[12:13], 9, v[12:13]
	v_lshl_add_u64 v[12:13], v[2:3], 0, v[12:13]
	global_load_ushort v10, v[12:13], off
	s_waitcnt vmcnt(0)
	v_lshlrev_b32_e32 v10, 16, v10
	v_fma_f32 v44, v11, v10, v43
	s_and_saveexec_b64 s[22:23], s[16:17]
	s_cbranch_execz .LBB0_1805
	global_load_ushort v10, v[12:13], off offset:-2
	global_load_dword v45, v1, s[20:21]
	s_waitcnt vmcnt(1)
	v_lshlrev_b32_e32 v10, 16, v10
	s_waitcnt vmcnt(0)
	v_fmac_f32_e32 v44, v45, v10

.LBB0_1806:
	ds_read_b128 v[50:53], v10
	ds_read_b128 v[54:57], v10 offset:16
	ds_read2_b32 v[58:59], v48 offset0:6 offset1:7
	ds_read2_b32 v[120:121], v48 offset0:4 offset1:5
	ds_read2_b32 v[122:123], v48 offset0:2 offset1:3
	ds_read2_b32 v[124:125], v48 offset1:1
	s_add_i32 s19, s19, 8
	v_mov_b32_e32 v47, v49
	v_cmp_eq_u32_e32 vcc, s19, v21
	v_add_u32_e32 v10, 32, v10
	s_waitcnt lgkmcnt(0)
	v_fmac_f32_e32 v45, v50, v59
	v_fmac_f32_e32 v45, v51, v58
	v_subrev_u32_e32 v49, 32, v47
	s_or_b64 s[22:23], vcc, s[22:23]
	v_fmac_f32_e32 v45, v52, v121
	v_fmac_f32_e32 v45, v53, v120
	v_fmac_f32_e32 v45, v54, v123
	v_fmac_f32_e32 v45, v55, v122
	v_subrev_u32_e32 v48, 32, v48
	v_fmac_f32_e32 v45, v56, v125
	v_fmac_f32_e32 v45, v57, v124
	s_andn2_b64 exec, exec, s[22:23]
	s_cbranch_execnz .LBB0_1806
	s_or_b64 exec, exec, s[22:23]
	s_and_saveexec_b64 s[22:23], s[14:15]
	s_cbranch_execz .LBB0_1811
	s_mov_b32 s19, 0
	s_mov_b64 s[24:25], 0

.LBB0_1811:
	s_or_b64 exec, exec, s[22:23]
	s_and_saveexec_b64 s[22:23], s[8:9]
	s_cbranch_execz .LBB0_1815
	s_add_i32 s19, 0, 0xc04
	s_mov_b64 s[24:25], 0
	v_mov_b32_e32 v10, v29
	v_mov_b32_e32 v100, s19
	s_movk_i32 s100, 0x600
	s_mov_b64 s[98:99], exec
	v_cmp_gt_i32_e32 vcc, 0xf7, v10
	s_and_b64 exec, exec, vcc
	s_cbranch_execz .Lhc3_rem
.Lhc3_main:
	v_add3_u32 v101, v100, v25, s100
	v_mov_b32_e32 v102, v100
	ds_read2_b32 v[104:105], v101 offset1:1
	ds_read2_b32 v[106:107], v101 offset0:2 offset1:3
	ds_read2_b32 v[108:109], v101 offset0:4 offset1:5
	ds_read2_b32 v[110:111], v101 offset0:6 offset1:7
	ds_read2_b32 v[112:113], v102 offset1:1
	ds_read2_b32 v[114:115], v102 offset0:2 offset1:3
	ds_read2_b32 v[116:117], v102 offset0:4 offset1:5
	ds_read2_b32 v[118:119], v102 offset0:6 offset1:7
	v_add_u32_e32 v10, 8, v10
	v_add_u32_e32 v100, 32, v100
	v_cmp_gt_i32_e32 vcc, 0xf7, v10
	s_waitcnt lgkmcnt(0)
	v_fmac_f32_e32 v45, v104, v112
	v_fmac_f32_e32 v45, v105, v113
	v_fmac_f32_e32 v45, v106, v114
	v_fmac_f32_e32 v45, v107, v115
	v_fmac_f32_e32 v45, v108, v116
	v_fmac_f32_e32 v45, v109, v117
	v_fmac_f32_e32 v45, v110, v118
	v_fmac_f32_e32 v45, v111, v119
	s_and_b64 exec, exec, vcc
	s_cbranch_execnz .Lhc3_main

.Lhc3_rl:
	v_add3_u32 v101, v100, v25, s100
	v_mov_b32_e32 v102, v100
	ds_read_b32 v101, v101
	ds_read_b32 v102, v102
	v_add_u32_e32 v10, 1, v10
	v_add_u32_e32 v100, 4, v100
	v_cmp_gt_i32_e32 vcc, 0xfe, v10
	s_waitcnt lgkmcnt(0)
	v_fmac_f32_e32 v45, v101, v102
	s_and_b64 exec, exec, vcc
	s_cbranch_execnz .Lhc3_rl
.Lhc3_end:
	s_mov_b64 exec, s[98:99]
	s_or_b64 exec, exec, s[24:25]

	.amdhsa_kernel _Z10fwd_kernel4Args
		.amdhsa_group_segment_fixed_size 0
		.amdhsa_private_segment_fixed_size 0
		.amdhsa_kernarg_size 528
		.amdhsa_user_sgpr_count 2
		.amdhsa_user_sgpr_dispatch_ptr 0
		.amdhsa_user_sgpr_queue_ptr 0
		.amdhsa_user_sgpr_kernarg_segment_ptr 1
		.amdhsa_user_sgpr_dispatch_id 0
		.amdhsa_user_sgpr_kernarg_preload_length 0
		.amdhsa_user_sgpr_kernarg_preload_offset 0
		.amdhsa_user_sgpr_private_segment_size 0
		.amdhsa_uses_dynamic_stack 0
		.amdhsa_enable_private_segment 0
		.amdhsa_system_sgpr_workgroup_id_x 1
		.amdhsa_system_sgpr_workgroup_id_y 0
		.amdhsa_system_sgpr_workgroup_id_z 0
		.amdhsa_system_sgpr_workgroup_info 0
		.amdhsa_system_vgpr_workitem_id 2
		.amdhsa_next_free_vgpr 254
		.amdhsa_next_free_sgpr 102
		.amdhsa_accum_offset 256
		.amdhsa_reserve_vcc 1
		.amdhsa_float_round_mode_32 0
		.amdhsa_float_round_mode_16_64 0
		.amdhsa_float_denorm_mode_32 3
		.amdhsa_float_denorm_mode_16_64 3
		.amdhsa_dx10_clamp 1
		.amdhsa_ieee_mode 1
		.amdhsa_fp16_overflow 0
		.amdhsa_tg_split 0
		.amdhsa_exception_fp_ieee_invalid_op 0
		.amdhsa_exception_fp_denorm_src 0
		.amdhsa_exception_fp_ieee_div_zero 0
		.amdhsa_exception_fp_ieee_overflow 0
		.amdhsa_exception_fp_ieee_underflow 0
		.amdhsa_exception_fp_ieee_inexact 0
		.amdhsa_exception_int_div_zero 0
	.end_amdhsa_kernel

amdhsa.kernels:
  - .agpr_count:     0
    .args:
      - .offset:         0
        .size:           272
        .value_kind:     by_value
      - .offset:         272
        .size:           4
        .value_kind:     hidden_block_count_x
      - .offset:         276
        .size:           4
        .value_kind:     hidden_block_count_y
      - .offset:         280
        .size:           4
        .value_kind:     hidden_block_count_z
      - .offset:         284
        .size:           2
        .value_kind:     hidden_group_size_x
      - .offset:         286
        .size:           2
        .value_kind:     hidden_group_size_y
      - .offset:         288
        .size:           2
        .value_kind:     hidden_group_size_z
      - .offset:         290
        .size:           2
        .value_kind:     hidden_remainder_x
      - .offset:         292
        .size:           2
        .value_kind:     hidden_remainder_y
      - .offset:         294
        .size:           2
        .value_kind:     hidden_remainder_z
      - .offset:         312
        .size:           8
        .value_kind:     hidden_global_offset_x
      - .offset:         320
        .size:           8
        .value_kind:     hidden_global_offset_y
      - .offset:         328
        .size:           8
        .value_kind:     hidden_global_offset_z
      - .offset:         336
        .size:           2
        .value_kind:     hidden_grid_dims
      - .offset:         360
        .size:           8
        .value_kind:     hidden_multigrid_sync_arg
      - .offset:         392
        .size:           4
        .value_kind:     hidden_dynamic_lds_size
    .group_segment_fixed_size: 0
    .kernarg_segment_align: 8
    .kernarg_segment_size: 528
    .language:       OpenCL C
    .language_version:
      - 2
      - 0
    .max_flat_workgroup_size: 512
    .name:           _Z10fwd_kernel4Args
    .private_segment_fixed_size: 0
    .sgpr_count:     108
    .sgpr_spill_count: 244
    .symbol:         _Z10fwd_kernel4Args.kd
    .uniform_work_group_size: 1
    .uses_dynamic_stack: false
    .vgpr_count:     254
    .vgpr_spill_count: 0
    .wavefront_size: 64
